# up-projection epilogue: first/last row groups use DPP row_shr/row_shl with zero fill instead of a select, packed +1.0 add
# baseline (speedup 1.0000x reference)
.LBB0_1151:
	v_readlane_b32 s51, v251, 4
	s_andn2_b64 vcc, exec, s[40:41]
	s_cbranch_vccnz .LBB0_1173
	s_nop 7
	s_nop 7
	v_lshl_or_b32 v176, s38, 7, v206
	v_lshlrev_b32_e32 v177, 2, v176
	v_add_u32_e32 v178, 0x5800, v177
	v_add_u32_e32 v179, 0xb000, v177
	global_load_dwordx4 v[102:105], v177, s[20:21]
	global_load_dwordx4 v[106:109], v177, s[20:21] offset:16
	global_load_dwordx4 v[110:113], v178, s[20:21]
	global_load_dwordx4 v[114:117], v178, s[20:21] offset:16
	global_load_dwordx4 v[118:121], v179, s[20:21]
	global_load_dwordx4 v[122:125], v179, s[20:21] offset:16
	global_load_dwordx4 v[126:129], v177, s[22:23]
	global_load_dwordx4 v[80:83], v177, s[22:23] offset:16
	v_lshlrev_b32_e32 v175, 1, v176
	s_lshl_b32 s40, s58, 8
	s_add_i32 s40, s40, s70
	s_movk_i32 s44, 0x2c00
	v_or_b32_e32 v174, s40, v192
	v_mov_b32_e32 v208, 0xbdd2d3e7
	s_mov_b32 s42, s31
	s_mov_b32 s43, s90
	s_ashr_i32 s41, s40, 4
	s_and_saveexec_b64 s[38:39], s[12:13]
	v_or_b32_e32 v176, s41, v192
	v_mad_u32_u24 v176, v176, s44, v175
	v_cvt_pk_bf16_f32 v188, v92, v93
	v_cvt_pk_bf16_f32 v189, v94, v95
	v_cvt_pk_bf16_f32 v190, v84, v85
	v_cvt_pk_bf16_f32 v191, v86, v87
	global_store_dwordx4 v176, v[188:191], s[62:63]
	s_and_b64 exec, exec, s[4:5]
	s_ashr_i32 s41, s40, 5
	s_mul_i32 s41, s41, s44
	v_add_u32_e32 v177, s41, v175
	v_cvt_pk_bf16_f32 v180, v98, v99
	v_cvt_pk_bf16_f32 v181, v100, v101
	v_cvt_pk_bf16_f32 v182, v88, v89
	v_cvt_pk_bf16_f32 v183, v90, v91
	global_store_dwordx4 v177, v[180:183], s[42:43]
	s_or_b64 exec, exec, s[38:39]
	s_ashr_i32 s41, s40, 4
	s_and_saveexec_b64 s[38:39], s[14:15]
	v_add_u32_e32 v178, s41, v205
	v_mad_u32_u24 v178, v178, s44, v175
	v_cvt_pk_bf16_f32 v184, v72, v73
	v_cvt_pk_bf16_f32 v185, v74, v75
	v_cvt_pk_bf16_f32 v186, v64, v65
	v_cvt_pk_bf16_f32 v187, v66, v67
	global_store_dwordx4 v178, v[184:187], s[62:63]
	s_and_b64 exec, exec, s[8:9]
	s_ashr_i32 s41, s40, 5
	s_or_b32 s41, s41, 1
	s_mul_i32 s41, s41, s44
	v_add_u32_e32 v179, s41, v175
	v_cvt_pk_bf16_f32 v188, v76, v77
	v_cvt_pk_bf16_f32 v189, v78, v79
	v_cvt_pk_bf16_f32 v190, v68, v69
	v_cvt_pk_bf16_f32 v191, v70, v71
	global_store_dwordx4 v179, v[188:191], s[42:43]
	s_or_b64 exec, exec, s[38:39]
	s_addk_i32 s40, 0x80
	s_ashr_i32 s41, s40, 4
	s_and_saveexec_b64 s[38:39], s[12:13]
	v_or_b32_e32 v176, s41, v192
	v_mad_u32_u24 v176, v176, s44, v175
	v_cvt_pk_bf16_f32 v188, v24, v25
	v_cvt_pk_bf16_f32 v189, v26, v27
	v_cvt_pk_bf16_f32 v190, v16, v17
	v_cvt_pk_bf16_f32 v191, v18, v19
	global_store_dwordx4 v176, v[188:191], s[62:63]
	s_and_b64 exec, exec, s[4:5]
	s_ashr_i32 s41, s40, 5
	s_mul_i32 s41, s41, s44
	v_add_u32_e32 v177, s41, v175
	v_cvt_pk_bf16_f32 v180, v28, v29
	v_cvt_pk_bf16_f32 v181, v30, v31
	v_cvt_pk_bf16_f32 v182, v20, v21
	v_cvt_pk_bf16_f32 v183, v22, v23
	global_store_dwordx4 v177, v[180:183], s[42:43]
	s_or_b64 exec, exec, s[38:39]
	s_ashr_i32 s41, s40, 4
	s_and_saveexec_b64 s[38:39], s[14:15]
	v_add_u32_e32 v178, s41, v205
	v_mad_u32_u24 v178, v178, s44, v175
	v_cvt_pk_bf16_f32 v184, v8, v9
	v_cvt_pk_bf16_f32 v185, v10, v11
	v_cvt_pk_bf16_f32 v186, v0, v1
	v_cvt_pk_bf16_f32 v187, v2, v3
	global_store_dwordx4 v178, v[184:187], s[62:63]
	s_and_b64 exec, exec, s[8:9]
	s_ashr_i32 s41, s40, 5
	s_or_b32 s41, s41, 1
	s_mul_i32 s41, s41, s44
	v_add_u32_e32 v179, s41, v175
	v_cvt_pk_bf16_f32 v188, v12, v13
	v_cvt_pk_bf16_f32 v189, v14, v15
	v_cvt_pk_bf16_f32 v190, v4, v5
	v_cvt_pk_bf16_f32 v191, v6, v7
	global_store_dwordx4 v179, v[188:191], s[42:43]
	s_or_b64 exec, exec, s[38:39]
	s_mov_b32 s40, 0xc0135761
	s_mov_b32 s41, 1.0
	s_waitcnt vmcnt(8)
	v_cndmask_b32_e64 v180, v92, v150, s[4:5]
	v_cndmask_b32_e64 v181, v93, v151, s[4:5]
	v_cndmask_b32_e64 v182, v94, v152, s[4:5]
	v_cndmask_b32_e64 v183, v95, v153, s[4:5]
	v_pk_fma_f32 v[184:185], v[110:111], v[92:93], v[126:127]
	v_pk_fma_f32 v[186:187], v[112:113], v[94:95], v[128:129]
	v_fmac_f32_dpp v184, v92, v102 row_shr:1 row_mask:0xf bank_mask:0xf bound_ctrl:0
	v_fmac_f32_dpp v185, v93, v103 row_shr:1 row_mask:0xf bank_mask:0xf bound_ctrl:0
	v_fmac_f32_dpp v186, v94, v104 row_shr:1 row_mask:0xf bank_mask:0xf bound_ctrl:0
	v_fmac_f32_dpp v187, v95, v105 row_shr:1 row_mask:0xf bank_mask:0xf bound_ctrl:0
	v_fmac_f32_dpp v184, v180, v118 row_ror:15 row_mask:0xf bank_mask:0xf
	v_fmac_f32_dpp v185, v181, v119 row_ror:15 row_mask:0xf bank_mask:0xf
	v_fmac_f32_dpp v186, v182, v120 row_ror:15 row_mask:0xf bank_mask:0xf
	v_fmac_f32_dpp v187, v183, v121 row_ror:15 row_mask:0xf bank_mask:0xf
	v_pk_mul_f32 v[176:177], v[184:185], v[184:185]
	v_pk_mul_f32 v[178:179], v[186:187], v[186:187]
	v_pk_fma_f32 v[176:177], v[176:177], v[208:209], s[40:41] op_sel_hi:[1,0,0]
	v_pk_fma_f32 v[178:179], v[178:179], v[208:209], s[40:41] op_sel_hi:[1,0,0]
	v_pk_mul_f32 v[176:177], v[176:177], v[184:185]
	v_pk_mul_f32 v[178:179], v[178:179], v[186:187]
	v_exp_f32_e32 v176, v176
	v_exp_f32_e32 v177, v177
	v_exp_f32_e32 v178, v178
	v_exp_f32_e32 v179, v179
	v_pk_add_f32 v[176:177], v[176:177], s[40:41] op_sel:[0,1] op_sel_hi:[1,1]
	v_pk_add_f32 v[178:179], v[178:179], s[40:41] op_sel:[0,1] op_sel_hi:[1,1]
	v_rcp_f32_e32 v176, v176
	v_rcp_f32_e32 v177, v177
	v_rcp_f32_e32 v178, v178
	v_rcp_f32_e32 v179, v179
	v_pk_mul_f32 v[184:185], v[184:185], v[176:177]
	v_pk_mul_f32 v[186:187], v[186:187], v[178:179]
	v_pk_mul_f32 v[184:185], v[184:185], v[98:99]
	v_pk_mul_f32 v[186:187], v[186:187], v[100:101]
	v_cvt_pk_bf16_f32 v188, v184, v185
	v_cvt_pk_bf16_f32 v189, v186, v187
	v_cndmask_b32_e64 v180, v84, v142, s[4:5]
	v_cndmask_b32_e64 v181, v85, v143, s[4:5]
	v_cndmask_b32_e64 v182, v86, v144, s[4:5]
	v_cndmask_b32_e64 v183, v87, v145, s[4:5]
	v_pk_fma_f32 v[184:185], v[114:115], v[84:85], v[80:81]
	v_pk_fma_f32 v[186:187], v[116:117], v[86:87], v[82:83]
	v_fmac_f32_dpp v184, v84, v106 row_shr:1 row_mask:0xf bank_mask:0xf bound_ctrl:0
	v_fmac_f32_dpp v185, v85, v107 row_shr:1 row_mask:0xf bank_mask:0xf bound_ctrl:0
	v_fmac_f32_dpp v186, v86, v108 row_shr:1 row_mask:0xf bank_mask:0xf bound_ctrl:0
	v_fmac_f32_dpp v187, v87, v109 row_shr:1 row_mask:0xf bank_mask:0xf bound_ctrl:0
	v_fmac_f32_dpp v184, v180, v122 row_ror:15 row_mask:0xf bank_mask:0xf
	v_fmac_f32_dpp v185, v181, v123 row_ror:15 row_mask:0xf bank_mask:0xf
	v_fmac_f32_dpp v186, v182, v124 row_ror:15 row_mask:0xf bank_mask:0xf
	v_fmac_f32_dpp v187, v183, v125 row_ror:15 row_mask:0xf bank_mask:0xf
	v_pk_mul_f32 v[176:177], v[184:185], v[184:185]
	v_pk_mul_f32 v[178:179], v[186:187], v[186:187]
	v_pk_fma_f32 v[176:177], v[176:177], v[208:209], s[40:41] op_sel_hi:[1,0,0]
	v_pk_fma_f32 v[178:179], v[178:179], v[208:209], s[40:41] op_sel_hi:[1,0,0]
	v_pk_mul_f32 v[176:177], v[176:177], v[184:185]
	v_pk_mul_f32 v[178:179], v[178:179], v[186:187]
	v_exp_f32_e32 v176, v176
	v_exp_f32_e32 v177, v177
	v_exp_f32_e32 v178, v178
	v_exp_f32_e32 v179, v179
	v_pk_add_f32 v[176:177], v[176:177], s[40:41] op_sel:[0,1] op_sel_hi:[1,1]
	v_pk_add_f32 v[178:179], v[178:179], s[40:41] op_sel:[0,1] op_sel_hi:[1,1]
	v_rcp_f32_e32 v176, v176
	v_rcp_f32_e32 v177, v177
	v_rcp_f32_e32 v178, v178
	v_rcp_f32_e32 v179, v179
	v_pk_mul_f32 v[184:185], v[184:185], v[176:177]
	v_pk_mul_f32 v[186:187], v[186:187], v[178:179]
	v_pk_mul_f32 v[184:185], v[184:185], v[88:89]
	v_pk_mul_f32 v[186:187], v[186:187], v[90:91]
	v_cvt_pk_bf16_f32 v190, v184, v185
	v_cvt_pk_bf16_f32 v191, v186, v187
	v_mov_b32_e32 v176, v174
	v_mad_u32_u24 v176, v176, s44, v175
	s_and_saveexec_b64 s[38:39], s[6:7]
	global_store_dwordx4 v176, v[188:191], s[54:55]
	s_or_b64 exec, exec, s[38:39]
	v_cndmask_b32_e64 v176, v150, v92, s[8:9]
	v_cndmask_b32_e64 v177, v151, v93, s[8:9]
	v_cndmask_b32_e64 v178, v152, v94, s[8:9]
	v_cndmask_b32_e64 v179, v153, v95, s[8:9]
	v_cndmask_b32_e64 v180, v150, v134, s[4:5]
	v_cndmask_b32_e64 v181, v151, v135, s[4:5]
	v_cndmask_b32_e64 v182, v152, v136, s[4:5]
	v_cndmask_b32_e64 v183, v153, v137, s[4:5]
	v_pk_fma_f32 v[184:185], v[110:111], v[150:151], v[126:127]
	v_pk_fma_f32 v[186:187], v[112:113], v[152:153], v[128:129]
	v_fmac_f32_dpp v184, v176, v102 row_ror:1 row_mask:0xf bank_mask:0xf
	v_fmac_f32_dpp v185, v177, v103 row_ror:1 row_mask:0xf bank_mask:0xf
	v_fmac_f32_dpp v186, v178, v104 row_ror:1 row_mask:0xf bank_mask:0xf
	v_fmac_f32_dpp v187, v179, v105 row_ror:1 row_mask:0xf bank_mask:0xf
	v_fmac_f32_dpp v184, v180, v118 row_ror:15 row_mask:0xf bank_mask:0xf
	v_fmac_f32_dpp v185, v181, v119 row_ror:15 row_mask:0xf bank_mask:0xf
	v_fmac_f32_dpp v186, v182, v120 row_ror:15 row_mask:0xf bank_mask:0xf
	v_fmac_f32_dpp v187, v183, v121 row_ror:15 row_mask:0xf bank_mask:0xf
	v_pk_mul_f32 v[176:177], v[184:185], v[184:185]
	v_pk_mul_f32 v[178:179], v[186:187], v[186:187]
	v_pk_fma_f32 v[176:177], v[176:177], v[208:209], s[40:41] op_sel_hi:[1,0,0]
	v_pk_fma_f32 v[178:179], v[178:179], v[208:209], s[40:41] op_sel_hi:[1,0,0]
	v_pk_mul_f32 v[176:177], v[176:177], v[184:185]
	v_pk_mul_f32 v[178:179], v[178:179], v[186:187]
	v_exp_f32_e32 v176, v176
	v_exp_f32_e32 v177, v177
	v_exp_f32_e32 v178, v178
	v_exp_f32_e32 v179, v179
	v_pk_add_f32 v[176:177], v[176:177], s[40:41] op_sel:[0,1] op_sel_hi:[1,1]
	v_pk_add_f32 v[178:179], v[178:179], s[40:41] op_sel:[0,1] op_sel_hi:[1,1]
	v_rcp_f32_e32 v176, v176
	v_rcp_f32_e32 v177, v177
	v_rcp_f32_e32 v178, v178
	v_rcp_f32_e32 v179, v179
	v_pk_mul_f32 v[184:185], v[184:185], v[176:177]
	v_pk_mul_f32 v[186:187], v[186:187], v[178:179]
	v_pk_mul_f32 v[184:185], v[184:185], v[158:159]
	v_pk_mul_f32 v[186:187], v[186:187], v[160:161]
	v_cvt_pk_bf16_f32 v188, v184, v185
	v_cvt_pk_bf16_f32 v189, v186, v187
	v_cndmask_b32_e64 v176, v142, v84, s[8:9]
	v_cndmask_b32_e64 v177, v143, v85, s[8:9]
	v_cndmask_b32_e64 v178, v144, v86, s[8:9]
	v_cndmask_b32_e64 v179, v145, v87, s[8:9]
	v_cndmask_b32_e64 v180, v142, v130, s[4:5]
	v_cndmask_b32_e64 v181, v143, v131, s[4:5]
	v_cndmask_b32_e64 v182, v144, v132, s[4:5]
	v_cndmask_b32_e64 v183, v145, v133, s[4:5]
	v_pk_fma_f32 v[184:185], v[114:115], v[142:143], v[80:81]
	v_pk_fma_f32 v[186:187], v[116:117], v[144:145], v[82:83]
	v_fmac_f32_dpp v184, v176, v106 row_ror:1 row_mask:0xf bank_mask:0xf
	v_fmac_f32_dpp v185, v177, v107 row_ror:1 row_mask:0xf bank_mask:0xf
	v_fmac_f32_dpp v186, v178, v108 row_ror:1 row_mask:0xf bank_mask:0xf
	v_fmac_f32_dpp v187, v179, v109 row_ror:1 row_mask:0xf bank_mask:0xf
	v_fmac_f32_dpp v184, v180, v122 row_ror:15 row_mask:0xf bank_mask:0xf
	v_fmac_f32_dpp v185, v181, v123 row_ror:15 row_mask:0xf bank_mask:0xf
	v_fmac_f32_dpp v186, v182, v124 row_ror:15 row_mask:0xf bank_mask:0xf
	v_fmac_f32_dpp v187, v183, v125 row_ror:15 row_mask:0xf bank_mask:0xf
	v_pk_mul_f32 v[176:177], v[184:185], v[184:185]
	v_pk_mul_f32 v[178:179], v[186:187], v[186:187]
	v_pk_fma_f32 v[176:177], v[176:177], v[208:209], s[40:41] op_sel_hi:[1,0,0]
	v_pk_fma_f32 v[178:179], v[178:179], v[208:209], s[40:41] op_sel_hi:[1,0,0]
	v_pk_mul_f32 v[176:177], v[176:177], v[184:185]
	v_pk_mul_f32 v[178:179], v[178:179], v[186:187]
	v_exp_f32_e32 v176, v176
	v_exp_f32_e32 v177, v177
	v_exp_f32_e32 v178, v178
	v_exp_f32_e32 v179, v179
	v_pk_add_f32 v[176:177], v[176:177], s[40:41] op_sel:[0,1] op_sel_hi:[1,1]
	v_pk_add_f32 v[178:179], v[178:179], s[40:41] op_sel:[0,1] op_sel_hi:[1,1]
	v_rcp_f32_e32 v176, v176
	v_rcp_f32_e32 v177, v177
	v_rcp_f32_e32 v178, v178
	v_rcp_f32_e32 v179, v179
	v_pk_mul_f32 v[184:185], v[184:185], v[176:177]
	v_pk_mul_f32 v[186:187], v[186:187], v[178:179]
	v_pk_mul_f32 v[184:185], v[184:185], v[154:155]
	v_pk_mul_f32 v[186:187], v[186:187], v[156:157]
	v_cvt_pk_bf16_f32 v190, v184, v185
	v_cvt_pk_bf16_f32 v191, v186, v187
	v_or_b32_e32 v176, 16, v174
	v_mad_u32_u24 v176, v176, s44, v175
	global_store_dwordx4 v176, v[188:191], s[54:55]
	v_cndmask_b32_e64 v176, v134, v150, s[8:9]
	v_cndmask_b32_e64 v177, v135, v151, s[8:9]
	v_cndmask_b32_e64 v178, v136, v152, s[8:9]
	v_cndmask_b32_e64 v179, v137, v153, s[8:9]
	v_cndmask_b32_e64 v180, v134, v72, s[4:5]
	v_cndmask_b32_e64 v181, v135, v73, s[4:5]
	v_cndmask_b32_e64 v182, v136, v74, s[4:5]
	v_cndmask_b32_e64 v183, v137, v75, s[4:5]
	v_pk_fma_f32 v[184:185], v[110:111], v[134:135], v[126:127]
	v_pk_fma_f32 v[186:187], v[112:113], v[136:137], v[128:129]
	v_fmac_f32_dpp v184, v176, v102 row_ror:1 row_mask:0xf bank_mask:0xf
	v_fmac_f32_dpp v185, v177, v103 row_ror:1 row_mask:0xf bank_mask:0xf
	v_fmac_f32_dpp v186, v178, v104 row_ror:1 row_mask:0xf bank_mask:0xf
	v_fmac_f32_dpp v187, v179, v105 row_ror:1 row_mask:0xf bank_mask:0xf
	v_fmac_f32_dpp v184, v180, v118 row_ror:15 row_mask:0xf bank_mask:0xf
	v_fmac_f32_dpp v185, v181, v119 row_ror:15 row_mask:0xf bank_mask:0xf
	v_fmac_f32_dpp v186, v182, v120 row_ror:15 row_mask:0xf bank_mask:0xf
	v_fmac_f32_dpp v187, v183, v121 row_ror:15 row_mask:0xf bank_mask:0xf
	v_pk_mul_f32 v[176:177], v[184:185], v[184:185]
	v_pk_mul_f32 v[178:179], v[186:187], v[186:187]
	v_pk_fma_f32 v[176:177], v[176:177], v[208:209], s[40:41] op_sel_hi:[1,0,0]
	v_pk_fma_f32 v[178:179], v[178:179], v[208:209], s[40:41] op_sel_hi:[1,0,0]
	v_pk_mul_f32 v[176:177], v[176:177], v[184:185]
	v_pk_mul_f32 v[178:179], v[178:179], v[186:187]
	v_exp_f32_e32 v176, v176
	v_exp_f32_e32 v177, v177
	v_exp_f32_e32 v178, v178
	v_exp_f32_e32 v179, v179
	v_pk_add_f32 v[176:177], v[176:177], s[40:41] op_sel:[0,1] op_sel_hi:[1,1]
	v_pk_add_f32 v[178:179], v[178:179], s[40:41] op_sel:[0,1] op_sel_hi:[1,1]
	v_rcp_f32_e32 v176, v176
	v_rcp_f32_e32 v177, v177
	v_rcp_f32_e32 v178, v178
	v_rcp_f32_e32 v179, v179
	v_pk_mul_f32 v[184:185], v[184:185], v[176:177]
	v_pk_mul_f32 v[186:187], v[186:187], v[178:179]
	v_pk_mul_f32 v[184:185], v[184:185], v[146:147]
	v_pk_mul_f32 v[186:187], v[186:187], v[148:149]
	v_cvt_pk_bf16_f32 v188, v184, v185
	v_cvt_pk_bf16_f32 v189, v186, v187
	v_cndmask_b32_e64 v176, v130, v142, s[8:9]
	v_cndmask_b32_e64 v177, v131, v143, s[8:9]
	v_cndmask_b32_e64 v178, v132, v144, s[8:9]
	v_cndmask_b32_e64 v179, v133, v145, s[8:9]
	v_cndmask_b32_e64 v180, v130, v64, s[4:5]
	v_cndmask_b32_e64 v181, v131, v65, s[4:5]
	v_cndmask_b32_e64 v182, v132, v66, s[4:5]
	v_cndmask_b32_e64 v183, v133, v67, s[4:5]
	v_pk_fma_f32 v[184:185], v[114:115], v[130:131], v[80:81]
	v_pk_fma_f32 v[186:187], v[116:117], v[132:133], v[82:83]
	v_fmac_f32_dpp v184, v176, v106 row_ror:1 row_mask:0xf bank_mask:0xf
	v_fmac_f32_dpp v185, v177, v107 row_ror:1 row_mask:0xf bank_mask:0xf
	v_fmac_f32_dpp v186, v178, v108 row_ror:1 row_mask:0xf bank_mask:0xf
	v_fmac_f32_dpp v187, v179, v109 row_ror:1 row_mask:0xf bank_mask:0xf
	v_fmac_f32_dpp v184, v180, v122 row_ror:15 row_mask:0xf bank_mask:0xf
	v_fmac_f32_dpp v185, v181, v123 row_ror:15 row_mask:0xf bank_mask:0xf
	v_fmac_f32_dpp v186, v182, v124 row_ror:15 row_mask:0xf bank_mask:0xf
	v_fmac_f32_dpp v187, v183, v125 row_ror:15 row_mask:0xf bank_mask:0xf
	v_pk_mul_f32 v[176:177], v[184:185], v[184:185]
	v_pk_mul_f32 v[178:179], v[186:187], v[186:187]
	v_pk_fma_f32 v[176:177], v[176:177], v[208:209], s[40:41] op_sel_hi:[1,0,0]
	v_pk_fma_f32 v[178:179], v[178:179], v[208:209], s[40:41] op_sel_hi:[1,0,0]
	v_pk_mul_f32 v[176:177], v[176:177], v[184:185]
	v_pk_mul_f32 v[178:179], v[178:179], v[186:187]
	v_exp_f32_e32 v176, v176
	v_exp_f32_e32 v177, v177
	v_exp_f32_e32 v178, v178
	v_exp_f32_e32 v179, v179
	v_pk_add_f32 v[176:177], v[176:177], s[40:41] op_sel:[0,1] op_sel_hi:[1,1]
	v_pk_add_f32 v[178:179], v[178:179], s[40:41] op_sel:[0,1] op_sel_hi:[1,1]
	v_rcp_f32_e32 v176, v176
	v_rcp_f32_e32 v177, v177
	v_rcp_f32_e32 v178, v178
	v_rcp_f32_e32 v179, v179
	v_pk_mul_f32 v[184:185], v[184:185], v[176:177]
	v_pk_mul_f32 v[186:187], v[186:187], v[178:179]
	v_pk_mul_f32 v[184:185], v[184:185], v[138:139]
	v_pk_mul_f32 v[186:187], v[186:187], v[140:141]
	v_cvt_pk_bf16_f32 v190, v184, v185
	v_cvt_pk_bf16_f32 v191, v186, v187
	v_or_b32_e32 v176, 32, v174
	v_mad_u32_u24 v176, v176, s44, v175
	global_store_dwordx4 v176, v[188:191], s[54:55]
	v_cndmask_b32_e64 v176, v72, v134, s[8:9]
	v_cndmask_b32_e64 v177, v73, v135, s[8:9]
	v_cndmask_b32_e64 v178, v74, v136, s[8:9]
	v_cndmask_b32_e64 v179, v75, v137, s[8:9]
	v_pk_fma_f32 v[184:185], v[110:111], v[72:73], v[126:127]
	v_pk_fma_f32 v[186:187], v[112:113], v[74:75], v[128:129]
	v_fmac_f32_dpp v184, v176, v102 row_ror:1 row_mask:0xf bank_mask:0xf
	v_fmac_f32_dpp v185, v177, v103 row_ror:1 row_mask:0xf bank_mask:0xf
	v_fmac_f32_dpp v186, v178, v104 row_ror:1 row_mask:0xf bank_mask:0xf
	v_fmac_f32_dpp v187, v179, v105 row_ror:1 row_mask:0xf bank_mask:0xf
	v_fmac_f32_dpp v184, v72, v118 row_shl:1 row_mask:0xf bank_mask:0xf bound_ctrl:0
	v_fmac_f32_dpp v185, v73, v119 row_shl:1 row_mask:0xf bank_mask:0xf bound_ctrl:0
	v_fmac_f32_dpp v186, v74, v120 row_shl:1 row_mask:0xf bank_mask:0xf bound_ctrl:0
	v_fmac_f32_dpp v187, v75, v121 row_shl:1 row_mask:0xf bank_mask:0xf bound_ctrl:0
	v_pk_mul_f32 v[176:177], v[184:185], v[184:185]
	v_pk_mul_f32 v[178:179], v[186:187], v[186:187]
	v_pk_fma_f32 v[176:177], v[176:177], v[208:209], s[40:41] op_sel_hi:[1,0,0]
	v_pk_fma_f32 v[178:179], v[178:179], v[208:209], s[40:41] op_sel_hi:[1,0,0]
	v_pk_mul_f32 v[176:177], v[176:177], v[184:185]
	v_pk_mul_f32 v[178:179], v[178:179], v[186:187]
	v_exp_f32_e32 v176, v176
	v_exp_f32_e32 v177, v177
	v_exp_f32_e32 v178, v178
	v_exp_f32_e32 v179, v179
	v_pk_add_f32 v[176:177], v[176:177], s[40:41] op_sel:[0,1] op_sel_hi:[1,1]
	v_pk_add_f32 v[178:179], v[178:179], s[40:41] op_sel:[0,1] op_sel_hi:[1,1]
	v_rcp_f32_e32 v176, v176
	v_rcp_f32_e32 v177, v177
	v_rcp_f32_e32 v178, v178
	v_rcp_f32_e32 v179, v179
	v_pk_mul_f32 v[184:185], v[184:185], v[176:177]
	v_pk_mul_f32 v[186:187], v[186:187], v[178:179]
	v_pk_mul_f32 v[184:185], v[184:185], v[76:77]
	v_pk_mul_f32 v[186:187], v[186:187], v[78:79]
	v_cvt_pk_bf16_f32 v188, v184, v185
	v_cvt_pk_bf16_f32 v189, v186, v187
	v_cndmask_b32_e64 v176, v64, v130, s[8:9]
	v_cndmask_b32_e64 v177, v65, v131, s[8:9]
	v_cndmask_b32_e64 v178, v66, v132, s[8:9]
	v_cndmask_b32_e64 v179, v67, v133, s[8:9]
	v_pk_fma_f32 v[184:185], v[114:115], v[64:65], v[80:81]
	v_pk_fma_f32 v[186:187], v[116:117], v[66:67], v[82:83]
	v_fmac_f32_dpp v184, v176, v106 row_ror:1 row_mask:0xf bank_mask:0xf
	v_fmac_f32_dpp v185, v177, v107 row_ror:1 row_mask:0xf bank_mask:0xf
	v_fmac_f32_dpp v186, v178, v108 row_ror:1 row_mask:0xf bank_mask:0xf
	v_fmac_f32_dpp v187, v179, v109 row_ror:1 row_mask:0xf bank_mask:0xf
	v_fmac_f32_dpp v184, v64, v122 row_shl:1 row_mask:0xf bank_mask:0xf bound_ctrl:0
	v_fmac_f32_dpp v185, v65, v123 row_shl:1 row_mask:0xf bank_mask:0xf bound_ctrl:0
	v_fmac_f32_dpp v186, v66, v124 row_shl:1 row_mask:0xf bank_mask:0xf bound_ctrl:0
	v_fmac_f32_dpp v187, v67, v125 row_shl:1 row_mask:0xf bank_mask:0xf bound_ctrl:0
	v_pk_mul_f32 v[176:177], v[184:185], v[184:185]
	v_pk_mul_f32 v[178:179], v[186:187], v[186:187]
	v_pk_fma_f32 v[176:177], v[176:177], v[208:209], s[40:41] op_sel_hi:[1,0,0]
	v_pk_fma_f32 v[178:179], v[178:179], v[208:209], s[40:41] op_sel_hi:[1,0,0]
	v_pk_mul_f32 v[176:177], v[176:177], v[184:185]
	v_pk_mul_f32 v[178:179], v[178:179], v[186:187]
	v_exp_f32_e32 v176, v176
	v_exp_f32_e32 v177, v177
	v_exp_f32_e32 v178, v178
	v_exp_f32_e32 v179, v179
	v_pk_add_f32 v[176:177], v[176:177], s[40:41] op_sel:[0,1] op_sel_hi:[1,1]
	v_pk_add_f32 v[178:179], v[178:179], s[40:41] op_sel:[0,1] op_sel_hi:[1,1]
	v_rcp_f32_e32 v176, v176
	v_rcp_f32_e32 v177, v177
	v_rcp_f32_e32 v178, v178
	v_rcp_f32_e32 v179, v179
	v_pk_mul_f32 v[184:185], v[184:185], v[176:177]
	v_pk_mul_f32 v[186:187], v[186:187], v[178:179]
	v_pk_mul_f32 v[184:185], v[184:185], v[68:69]
	v_pk_mul_f32 v[186:187], v[186:187], v[70:71]
	v_cvt_pk_bf16_f32 v190, v184, v185
	v_cvt_pk_bf16_f32 v191, v186, v187
	v_or_b32_e32 v176, 48, v174
	v_mad_u32_u24 v176, v176, s44, v175
	s_and_saveexec_b64 s[38:39], s[10:11]
	global_store_dwordx4 v176, v[188:191], s[54:55]
	s_or_b64 exec, exec, s[38:39]
	v_cndmask_b32_e64 v180, v24, v52, s[4:5]
	v_cndmask_b32_e64 v181, v25, v53, s[4:5]
	v_cndmask_b32_e64 v182, v26, v54, s[4:5]
	v_cndmask_b32_e64 v183, v27, v55, s[4:5]
	v_pk_fma_f32 v[184:185], v[110:111], v[24:25], v[126:127]
	v_pk_fma_f32 v[186:187], v[112:113], v[26:27], v[128:129]
	v_fmac_f32_dpp v184, v24, v102 row_shr:1 row_mask:0xf bank_mask:0xf bound_ctrl:0
	v_fmac_f32_dpp v185, v25, v103 row_shr:1 row_mask:0xf bank_mask:0xf bound_ctrl:0
	v_fmac_f32_dpp v186, v26, v104 row_shr:1 row_mask:0xf bank_mask:0xf bound_ctrl:0
	v_fmac_f32_dpp v187, v27, v105 row_shr:1 row_mask:0xf bank_mask:0xf bound_ctrl:0
	v_fmac_f32_dpp v184, v180, v118 row_ror:15 row_mask:0xf bank_mask:0xf
	v_fmac_f32_dpp v185, v181, v119 row_ror:15 row_mask:0xf bank_mask:0xf
	v_fmac_f32_dpp v186, v182, v120 row_ror:15 row_mask:0xf bank_mask:0xf
	v_fmac_f32_dpp v187, v183, v121 row_ror:15 row_mask:0xf bank_mask:0xf
	v_pk_mul_f32 v[176:177], v[184:185], v[184:185]
	v_pk_mul_f32 v[178:179], v[186:187], v[186:187]
	v_pk_fma_f32 v[176:177], v[176:177], v[208:209], s[40:41] op_sel_hi:[1,0,0]
	v_pk_fma_f32 v[178:179], v[178:179], v[208:209], s[40:41] op_sel_hi:[1,0,0]
	v_pk_mul_f32 v[176:177], v[176:177], v[184:185]
	v_pk_mul_f32 v[178:179], v[178:179], v[186:187]
	v_exp_f32_e32 v176, v176
	v_exp_f32_e32 v177, v177
	v_exp_f32_e32 v178, v178
	v_exp_f32_e32 v179, v179
	v_pk_add_f32 v[176:177], v[176:177], s[40:41] op_sel:[0,1] op_sel_hi:[1,1]
	v_pk_add_f32 v[178:179], v[178:179], s[40:41] op_sel:[0,1] op_sel_hi:[1,1]
	v_rcp_f32_e32 v176, v176
	v_rcp_f32_e32 v177, v177
	v_rcp_f32_e32 v178, v178
	v_rcp_f32_e32 v179, v179
	v_pk_mul_f32 v[184:185], v[184:185], v[176:177]
	v_pk_mul_f32 v[186:187], v[186:187], v[178:179]
	v_pk_mul_f32 v[184:185], v[184:185], v[28:29]
	v_pk_mul_f32 v[186:187], v[186:187], v[30:31]
	v_cvt_pk_bf16_f32 v188, v184, v185
	v_cvt_pk_bf16_f32 v189, v186, v187
	v_cndmask_b32_e64 v180, v16, v44, s[4:5]
	v_cndmask_b32_e64 v181, v17, v45, s[4:5]
	v_cndmask_b32_e64 v182, v18, v46, s[4:5]
	v_cndmask_b32_e64 v183, v19, v47, s[4:5]
	v_pk_fma_f32 v[184:185], v[114:115], v[16:17], v[80:81]
	v_pk_fma_f32 v[186:187], v[116:117], v[18:19], v[82:83]
	v_fmac_f32_dpp v184, v16, v106 row_shr:1 row_mask:0xf bank_mask:0xf bound_ctrl:0
	v_fmac_f32_dpp v185, v17, v107 row_shr:1 row_mask:0xf bank_mask:0xf bound_ctrl:0
	v_fmac_f32_dpp v186, v18, v108 row_shr:1 row_mask:0xf bank_mask:0xf bound_ctrl:0
	v_fmac_f32_dpp v187, v19, v109 row_shr:1 row_mask:0xf bank_mask:0xf bound_ctrl:0
	v_fmac_f32_dpp v184, v180, v122 row_ror:15 row_mask:0xf bank_mask:0xf
	v_fmac_f32_dpp v185, v181, v123 row_ror:15 row_mask:0xf bank_mask:0xf
	v_fmac_f32_dpp v186, v182, v124 row_ror:15 row_mask:0xf bank_mask:0xf
	v_fmac_f32_dpp v187, v183, v125 row_ror:15 row_mask:0xf bank_mask:0xf
	v_pk_mul_f32 v[176:177], v[184:185], v[184:185]
	v_pk_mul_f32 v[178:179], v[186:187], v[186:187]
	v_pk_fma_f32 v[176:177], v[176:177], v[208:209], s[40:41] op_sel_hi:[1,0,0]
	v_pk_fma_f32 v[178:179], v[178:179], v[208:209], s[40:41] op_sel_hi:[1,0,0]
	v_pk_mul_f32 v[176:177], v[176:177], v[184:185]
	v_pk_mul_f32 v[178:179], v[178:179], v[186:187]
	v_exp_f32_e32 v176, v176
	v_exp_f32_e32 v177, v177
	v_exp_f32_e32 v178, v178
	v_exp_f32_e32 v179, v179
	v_pk_add_f32 v[176:177], v[176:177], s[40:41] op_sel:[0,1] op_sel_hi:[1,1]
	v_pk_add_f32 v[178:179], v[178:179], s[40:41] op_sel:[0,1] op_sel_hi:[1,1]
	v_rcp_f32_e32 v176, v176
	v_rcp_f32_e32 v177, v177
	v_rcp_f32_e32 v178, v178
	v_rcp_f32_e32 v179, v179
	v_pk_mul_f32 v[184:185], v[184:185], v[176:177]
	v_pk_mul_f32 v[186:187], v[186:187], v[178:179]
	v_pk_mul_f32 v[184:185], v[184:185], v[20:21]
	v_pk_mul_f32 v[186:187], v[186:187], v[22:23]
	v_cvt_pk_bf16_f32 v190, v184, v185
	v_cvt_pk_bf16_f32 v191, v186, v187
	v_or_b32_e32 v176, 0x80, v174
	v_mad_u32_u24 v176, v176, s44, v175
	s_and_saveexec_b64 s[38:39], s[6:7]
	global_store_dwordx4 v176, v[188:191], s[54:55]
	s_or_b64 exec, exec, s[38:39]
	v_cndmask_b32_e64 v176, v52, v24, s[8:9]
	v_cndmask_b32_e64 v177, v53, v25, s[8:9]
	v_cndmask_b32_e64 v178, v54, v26, s[8:9]
	v_cndmask_b32_e64 v179, v55, v27, s[8:9]
	v_cndmask_b32_e64 v180, v52, v36, s[4:5]
	v_cndmask_b32_e64 v181, v53, v37, s[4:5]
	v_cndmask_b32_e64 v182, v54, v38, s[4:5]
	v_cndmask_b32_e64 v183, v55, v39, s[4:5]
	v_pk_fma_f32 v[184:185], v[110:111], v[52:53], v[126:127]
	v_pk_fma_f32 v[186:187], v[112:113], v[54:55], v[128:129]
	v_fmac_f32_dpp v184, v176, v102 row_ror:1 row_mask:0xf bank_mask:0xf
	v_fmac_f32_dpp v185, v177, v103 row_ror:1 row_mask:0xf bank_mask:0xf
	v_fmac_f32_dpp v186, v178, v104 row_ror:1 row_mask:0xf bank_mask:0xf
	v_fmac_f32_dpp v187, v179, v105 row_ror:1 row_mask:0xf bank_mask:0xf
	v_fmac_f32_dpp v184, v180, v118 row_ror:15 row_mask:0xf bank_mask:0xf
	v_fmac_f32_dpp v185, v181, v119 row_ror:15 row_mask:0xf bank_mask:0xf
	v_fmac_f32_dpp v186, v182, v120 row_ror:15 row_mask:0xf bank_mask:0xf
	v_fmac_f32_dpp v187, v183, v121 row_ror:15 row_mask:0xf bank_mask:0xf
	v_pk_mul_f32 v[176:177], v[184:185], v[184:185]
	v_pk_mul_f32 v[178:179], v[186:187], v[186:187]
	v_pk_fma_f32 v[176:177], v[176:177], v[208:209], s[40:41] op_sel_hi:[1,0,0]
	v_pk_fma_f32 v[178:179], v[178:179], v[208:209], s[40:41] op_sel_hi:[1,0,0]
	v_pk_mul_f32 v[176:177], v[176:177], v[184:185]
	v_pk_mul_f32 v[178:179], v[178:179], v[186:187]
	v_exp_f32_e32 v176, v176
	v_exp_f32_e32 v177, v177
	v_exp_f32_e32 v178, v178
	v_exp_f32_e32 v179, v179
	v_pk_add_f32 v[176:177], v[176:177], s[40:41] op_sel:[0,1] op_sel_hi:[1,1]
	v_pk_add_f32 v[178:179], v[178:179], s[40:41] op_sel:[0,1] op_sel_hi:[1,1]
	v_rcp_f32_e32 v176, v176
	v_rcp_f32_e32 v177, v177
	v_rcp_f32_e32 v178, v178
	v_rcp_f32_e32 v179, v179
	v_pk_mul_f32 v[184:185], v[184:185], v[176:177]
	v_pk_mul_f32 v[186:187], v[186:187], v[178:179]
	v_pk_mul_f32 v[184:185], v[184:185], v[60:61]
	v_pk_mul_f32 v[186:187], v[186:187], v[62:63]
	v_cvt_pk_bf16_f32 v188, v184, v185
	v_cvt_pk_bf16_f32 v189, v186, v187
	v_cndmask_b32_e64 v176, v44, v16, s[8:9]
	v_cndmask_b32_e64 v177, v45, v17, s[8:9]
	v_cndmask_b32_e64 v178, v46, v18, s[8:9]
	v_cndmask_b32_e64 v179, v47, v19, s[8:9]
	v_cndmask_b32_e64 v180, v44, v32, s[4:5]
	v_cndmask_b32_e64 v181, v45, v33, s[4:5]
	v_cndmask_b32_e64 v182, v46, v34, s[4:5]
	v_cndmask_b32_e64 v183, v47, v35, s[4:5]
	v_pk_fma_f32 v[184:185], v[114:115], v[44:45], v[80:81]
	v_pk_fma_f32 v[186:187], v[116:117], v[46:47], v[82:83]
	v_fmac_f32_dpp v184, v176, v106 row_ror:1 row_mask:0xf bank_mask:0xf
	v_fmac_f32_dpp v185, v177, v107 row_ror:1 row_mask:0xf bank_mask:0xf
	v_fmac_f32_dpp v186, v178, v108 row_ror:1 row_mask:0xf bank_mask:0xf
	v_fmac_f32_dpp v187, v179, v109 row_ror:1 row_mask:0xf bank_mask:0xf
	v_fmac_f32_dpp v184, v180, v122 row_ror:15 row_mask:0xf bank_mask:0xf
	v_fmac_f32_dpp v185, v181, v123 row_ror:15 row_mask:0xf bank_mask:0xf
	v_fmac_f32_dpp v186, v182, v124 row_ror:15 row_mask:0xf bank_mask:0xf
	v_fmac_f32_dpp v187, v183, v125 row_ror:15 row_mask:0xf bank_mask:0xf
	v_pk_mul_f32 v[176:177], v[184:185], v[184:185]
	v_pk_mul_f32 v[178:179], v[186:187], v[186:187]
	v_pk_fma_f32 v[176:177], v[176:177], v[208:209], s[40:41] op_sel_hi:[1,0,0]
	v_pk_fma_f32 v[178:179], v[178:179], v[208:209], s[40:41] op_sel_hi:[1,0,0]
	v_pk_mul_f32 v[176:177], v[176:177], v[184:185]
	v_pk_mul_f32 v[178:179], v[178:179], v[186:187]
	v_exp_f32_e32 v176, v176
	v_exp_f32_e32 v177, v177
	v_exp_f32_e32 v178, v178
	v_exp_f32_e32 v179, v179
	v_pk_add_f32 v[176:177], v[176:177], s[40:41] op_sel:[0,1] op_sel_hi:[1,1]
	v_pk_add_f32 v[178:179], v[178:179], s[40:41] op_sel:[0,1] op_sel_hi:[1,1]
	v_rcp_f32_e32 v176, v176
	v_rcp_f32_e32 v177, v177
	v_rcp_f32_e32 v178, v178
	v_rcp_f32_e32 v179, v179
	v_pk_mul_f32 v[184:185], v[184:185], v[176:177]
	v_pk_mul_f32 v[186:187], v[186:187], v[178:179]
	v_pk_mul_f32 v[184:185], v[184:185], v[56:57]
	v_pk_mul_f32 v[186:187], v[186:187], v[58:59]
	v_cvt_pk_bf16_f32 v190, v184, v185
	v_cvt_pk_bf16_f32 v191, v186, v187
	v_or_b32_e32 v176, 0x90, v174
	v_mad_u32_u24 v176, v176, s44, v175
	global_store_dwordx4 v176, v[188:191], s[54:55]
	v_cndmask_b32_e64 v176, v36, v52, s[8:9]
	v_cndmask_b32_e64 v177, v37, v53, s[8:9]
	v_cndmask_b32_e64 v178, v38, v54, s[8:9]
	v_cndmask_b32_e64 v179, v39, v55, s[8:9]
	v_cndmask_b32_e64 v180, v36, v8, s[4:5]
	v_cndmask_b32_e64 v181, v37, v9, s[4:5]
	v_cndmask_b32_e64 v182, v38, v10, s[4:5]
	v_cndmask_b32_e64 v183, v39, v11, s[4:5]
	v_pk_fma_f32 v[184:185], v[110:111], v[36:37], v[126:127]
	v_pk_fma_f32 v[186:187], v[112:113], v[38:39], v[128:129]
	v_fmac_f32_dpp v184, v176, v102 row_ror:1 row_mask:0xf bank_mask:0xf
	v_fmac_f32_dpp v185, v177, v103 row_ror:1 row_mask:0xf bank_mask:0xf
	v_fmac_f32_dpp v186, v178, v104 row_ror:1 row_mask:0xf bank_mask:0xf
	v_fmac_f32_dpp v187, v179, v105 row_ror:1 row_mask:0xf bank_mask:0xf
	v_fmac_f32_dpp v184, v180, v118 row_ror:15 row_mask:0xf bank_mask:0xf
	v_fmac_f32_dpp v185, v181, v119 row_ror:15 row_mask:0xf bank_mask:0xf
	v_fmac_f32_dpp v186, v182, v120 row_ror:15 row_mask:0xf bank_mask:0xf
	v_fmac_f32_dpp v187, v183, v121 row_ror:15 row_mask:0xf bank_mask:0xf
	v_pk_mul_f32 v[176:177], v[184:185], v[184:185]
	v_pk_mul_f32 v[178:179], v[186:187], v[186:187]
	v_pk_fma_f32 v[176:177], v[176:177], v[208:209], s[40:41] op_sel_hi:[1,0,0]
	v_pk_fma_f32 v[178:179], v[178:179], v[208:209], s[40:41] op_sel_hi:[1,0,0]
	v_pk_mul_f32 v[176:177], v[176:177], v[184:185]
	v_pk_mul_f32 v[178:179], v[178:179], v[186:187]
	v_exp_f32_e32 v176, v176
	v_exp_f32_e32 v177, v177
	v_exp_f32_e32 v178, v178
	v_exp_f32_e32 v179, v179
	v_pk_add_f32 v[176:177], v[176:177], s[40:41] op_sel:[0,1] op_sel_hi:[1,1]
	v_pk_add_f32 v[178:179], v[178:179], s[40:41] op_sel:[0,1] op_sel_hi:[1,1]
	v_rcp_f32_e32 v176, v176
	v_rcp_f32_e32 v177, v177
	v_rcp_f32_e32 v178, v178
	v_rcp_f32_e32 v179, v179
	v_pk_mul_f32 v[184:185], v[184:185], v[176:177]
	v_pk_mul_f32 v[186:187], v[186:187], v[178:179]
	v_pk_mul_f32 v[184:185], v[184:185], v[48:49]
	v_pk_mul_f32 v[186:187], v[186:187], v[50:51]
	v_cvt_pk_bf16_f32 v188, v184, v185
	v_cvt_pk_bf16_f32 v189, v186, v187
	v_cndmask_b32_e64 v176, v32, v44, s[8:9]
	v_cndmask_b32_e64 v177, v33, v45, s[8:9]
	v_cndmask_b32_e64 v178, v34, v46, s[8:9]
	v_cndmask_b32_e64 v179, v35, v47, s[8:9]
	v_cndmask_b32_e64 v180, v32, v0, s[4:5]
	v_cndmask_b32_e64 v181, v33, v1, s[4:5]
	v_cndmask_b32_e64 v182, v34, v2, s[4:5]
	v_cndmask_b32_e64 v183, v35, v3, s[4:5]
	v_pk_fma_f32 v[184:185], v[114:115], v[32:33], v[80:81]
	v_pk_fma_f32 v[186:187], v[116:117], v[34:35], v[82:83]
	v_fmac_f32_dpp v184, v176, v106 row_ror:1 row_mask:0xf bank_mask:0xf
	v_fmac_f32_dpp v185, v177, v107 row_ror:1 row_mask:0xf bank_mask:0xf
	v_fmac_f32_dpp v186, v178, v108 row_ror:1 row_mask:0xf bank_mask:0xf
	v_fmac_f32_dpp v187, v179, v109 row_ror:1 row_mask:0xf bank_mask:0xf
	v_fmac_f32_dpp v184, v180, v122 row_ror:15 row_mask:0xf bank_mask:0xf
	v_fmac_f32_dpp v185, v181, v123 row_ror:15 row_mask:0xf bank_mask:0xf
	v_fmac_f32_dpp v186, v182, v124 row_ror:15 row_mask:0xf bank_mask:0xf
	v_fmac_f32_dpp v187, v183, v125 row_ror:15 row_mask:0xf bank_mask:0xf
	v_pk_mul_f32 v[176:177], v[184:185], v[184:185]
	v_pk_mul_f32 v[178:179], v[186:187], v[186:187]
	v_pk_fma_f32 v[176:177], v[176:177], v[208:209], s[40:41] op_sel_hi:[1,0,0]
	v_pk_fma_f32 v[178:179], v[178:179], v[208:209], s[40:41] op_sel_hi:[1,0,0]
	v_pk_mul_f32 v[176:177], v[176:177], v[184:185]
	v_pk_mul_f32 v[178:179], v[178:179], v[186:187]
	v_exp_f32_e32 v176, v176
	v_exp_f32_e32 v177, v177
	v_exp_f32_e32 v178, v178
	v_exp_f32_e32 v179, v179
	v_pk_add_f32 v[176:177], v[176:177], s[40:41] op_sel:[0,1] op_sel_hi:[1,1]
	v_pk_add_f32 v[178:179], v[178:179], s[40:41] op_sel:[0,1] op_sel_hi:[1,1]
	v_rcp_f32_e32 v176, v176
	v_rcp_f32_e32 v177, v177
	v_rcp_f32_e32 v178, v178
	v_rcp_f32_e32 v179, v179
	v_pk_mul_f32 v[184:185], v[184:185], v[176:177]
	v_pk_mul_f32 v[186:187], v[186:187], v[178:179]
	v_pk_mul_f32 v[184:185], v[184:185], v[40:41]
	v_pk_mul_f32 v[186:187], v[186:187], v[42:43]
	v_cvt_pk_bf16_f32 v190, v184, v185
	v_cvt_pk_bf16_f32 v191, v186, v187
	v_or_b32_e32 v176, 0xa0, v174
	v_mad_u32_u24 v176, v176, s44, v175
	global_store_dwordx4 v176, v[188:191], s[54:55]
	v_cndmask_b32_e64 v176, v8, v36, s[8:9]
	v_cndmask_b32_e64 v177, v9, v37, s[8:9]
	v_cndmask_b32_e64 v178, v10, v38, s[8:9]
	v_cndmask_b32_e64 v179, v11, v39, s[8:9]
	v_pk_fma_f32 v[184:185], v[110:111], v[8:9], v[126:127]
	v_pk_fma_f32 v[186:187], v[112:113], v[10:11], v[128:129]
	v_fmac_f32_dpp v184, v176, v102 row_ror:1 row_mask:0xf bank_mask:0xf
	v_fmac_f32_dpp v185, v177, v103 row_ror:1 row_mask:0xf bank_mask:0xf
	v_fmac_f32_dpp v186, v178, v104 row_ror:1 row_mask:0xf bank_mask:0xf
	v_fmac_f32_dpp v187, v179, v105 row_ror:1 row_mask:0xf bank_mask:0xf
	v_fmac_f32_dpp v184, v8, v118 row_shl:1 row_mask:0xf bank_mask:0xf bound_ctrl:0
	v_fmac_f32_dpp v185, v9, v119 row_shl:1 row_mask:0xf bank_mask:0xf bound_ctrl:0
	v_fmac_f32_dpp v186, v10, v120 row_shl:1 row_mask:0xf bank_mask:0xf bound_ctrl:0
	v_fmac_f32_dpp v187, v11, v121 row_shl:1 row_mask:0xf bank_mask:0xf bound_ctrl:0
	v_pk_mul_f32 v[176:177], v[184:185], v[184:185]
	v_pk_mul_f32 v[178:179], v[186:187], v[186:187]
	v_pk_fma_f32 v[176:177], v[176:177], v[208:209], s[40:41] op_sel_hi:[1,0,0]
	v_pk_fma_f32 v[178:179], v[178:179], v[208:209], s[40:41] op_sel_hi:[1,0,0]
	v_pk_mul_f32 v[176:177], v[176:177], v[184:185]
	v_pk_mul_f32 v[178:179], v[178:179], v[186:187]
	v_exp_f32_e32 v176, v176
	v_exp_f32_e32 v177, v177
	v_exp_f32_e32 v178, v178
	v_exp_f32_e32 v179, v179
	v_pk_add_f32 v[176:177], v[176:177], s[40:41] op_sel:[0,1] op_sel_hi:[1,1]
	v_pk_add_f32 v[178:179], v[178:179], s[40:41] op_sel:[0,1] op_sel_hi:[1,1]
	v_rcp_f32_e32 v176, v176
	v_rcp_f32_e32 v177, v177
	v_rcp_f32_e32 v178, v178
	v_rcp_f32_e32 v179, v179
	v_pk_mul_f32 v[184:185], v[184:185], v[176:177]
	v_pk_mul_f32 v[186:187], v[186:187], v[178:179]
	v_pk_mul_f32 v[184:185], v[184:185], v[12:13]
	v_pk_mul_f32 v[186:187], v[186:187], v[14:15]
	v_cvt_pk_bf16_f32 v188, v184, v185
	v_cvt_pk_bf16_f32 v189, v186, v187
	v_cndmask_b32_e64 v176, v0, v32, s[8:9]
	v_cndmask_b32_e64 v177, v1, v33, s[8:9]
	v_cndmask_b32_e64 v178, v2, v34, s[8:9]
	v_cndmask_b32_e64 v179, v3, v35, s[8:9]
	v_pk_fma_f32 v[184:185], v[114:115], v[0:1], v[80:81]
	v_pk_fma_f32 v[186:187], v[116:117], v[2:3], v[82:83]
	v_fmac_f32_dpp v184, v176, v106 row_ror:1 row_mask:0xf bank_mask:0xf
	v_fmac_f32_dpp v185, v177, v107 row_ror:1 row_mask:0xf bank_mask:0xf
	v_fmac_f32_dpp v186, v178, v108 row_ror:1 row_mask:0xf bank_mask:0xf
	v_fmac_f32_dpp v187, v179, v109 row_ror:1 row_mask:0xf bank_mask:0xf
	v_fmac_f32_dpp v184, v0, v122 row_shl:1 row_mask:0xf bank_mask:0xf bound_ctrl:0
	v_fmac_f32_dpp v185, v1, v123 row_shl:1 row_mask:0xf bank_mask:0xf bound_ctrl:0
	v_fmac_f32_dpp v186, v2, v124 row_shl:1 row_mask:0xf bank_mask:0xf bound_ctrl:0
	v_fmac_f32_dpp v187, v3, v125 row_shl:1 row_mask:0xf bank_mask:0xf bound_ctrl:0
	v_pk_mul_f32 v[176:177], v[184:185], v[184:185]
	v_pk_mul_f32 v[178:179], v[186:187], v[186:187]
	v_pk_fma_f32 v[176:177], v[176:177], v[208:209], s[40:41] op_sel_hi:[1,0,0]
	v_pk_fma_f32 v[178:179], v[178:179], v[208:209], s[40:41] op_sel_hi:[1,0,0]
	v_pk_mul_f32 v[176:177], v[176:177], v[184:185]
	v_pk_mul_f32 v[178:179], v[178:179], v[186:187]
	v_exp_f32_e32 v176, v176
	v_exp_f32_e32 v177, v177
	v_exp_f32_e32 v178, v178
	v_exp_f32_e32 v179, v179
	v_pk_add_f32 v[176:177], v[176:177], s[40:41] op_sel:[0,1] op_sel_hi:[1,1]
	v_pk_add_f32 v[178:179], v[178:179], s[40:41] op_sel:[0,1] op_sel_hi:[1,1]
	v_rcp_f32_e32 v176, v176
	v_rcp_f32_e32 v177, v177
	v_rcp_f32_e32 v178, v178
	v_rcp_f32_e32 v179, v179
	v_pk_mul_f32 v[184:185], v[184:185], v[176:177]
	v_pk_mul_f32 v[186:187], v[186:187], v[178:179]
	v_pk_mul_f32 v[184:185], v[184:185], v[4:5]
	v_pk_mul_f32 v[186:187], v[186:187], v[6:7]
	v_cvt_pk_bf16_f32 v190, v184, v185
	v_cvt_pk_bf16_f32 v191, v186, v187
	v_or_b32_e32 v176, 0xb0, v174
	v_mad_u32_u24 v176, v176, s44, v175
	s_and_saveexec_b64 s[38:39], s[10:11]
	global_store_dwordx4 v176, v[188:191], s[54:55]
	s_or_b64 exec, exec, s[38:39]
